# phase-0 adaLN partial sums: w_ada row loads prefetched one iteration ahead
# speedup vs baseline: 1.0092x; 1.0002x over previous
; __device__ __forceinline__ void phase_init(const Params& p, LAS unsigned char* lds) {
;     ...
;         const int n = cb * 512 + tid; float acc[18];
; #pragma unroll
;         for (int s = 0; s < 18; ++s) acc[s] = 0.f;
;         const float* w = p.w_ada + (size_t)l * 1024 * 3072 + (size_t)(ks * 128) * 3072 + n;
; #pragma unroll 4
;         for (int k = 0; k < 128; ++k) { const float wv = w[(size_t)k * 3072];
; #pragma unroll
;             for (int s = 0; s < 18; ++s) acc[s] += tile[s * 128 + k] * wv; }
; #pragma unroll
.LBB0_675:
	s_or_b64 exec, exec, s[0:1]
	s_ashr_i32 s8, s10, 3
	s_mul_i32 s12, s12, 6
	s_add_i32 s8, s8, s11
	s_sub_i32 s0, s4, s12
	s_mul_i32 s1, s8, 0xc00000
	v_lshl_add_u32 v36, s0, 9, v94
	s_mul_hi_i32 s0, s8, 0xc00000
	s_add_u32 s9, s88, s1
	s_addc_u32 s10, s89, s0
	s_mul_i32 s0, s6, 0x60000
	s_ashr_i32 s1, s0, 31
	s_lshl_b64 s[0:1], s[0:1], 2
	s_add_u32 s0, s9, s0
	s_addc_u32 s1, s10, s1
	v_ashrrev_i32_e32 v37, 31, v36
	v_mov_b32_e32 v48, 0
	v_lshl_add_u64 v[38:39], v[36:37], 2, s[0:1]
	s_mov_b64 s[100:101], s[0:1]
	v_lshlrev_b32_e32 v110, 2, v36
	v_add_u32_e32 v111, 0x3000, v110
	v_add_u32_e32 v106, 0x6000, v110
	v_add_u32_e32 v107, 0x9000, v110
	global_load_dword v112, v110, s[100:101]
	global_load_dword v114, v111, s[100:101]
	global_load_dword v116, v106, s[100:101]
	global_load_dword v118, v107, s[100:101]
	s_mov_b64 s[0:1], 0
	s_mov_b32 s9, 0
	v_mov_b32_e32 v49, v48
	v_mov_b32_e32 v64, v48
	v_mov_b32_e32 v65, v48
	v_mov_b32_e32 v62, v48
	v_mov_b32_e32 v63, v48
	v_mov_b32_e32 v60, v48
	v_mov_b32_e32 v61, v48
	v_mov_b32_e32 v58, v48
	v_mov_b32_e32 v59, v48
	v_mov_b32_e32 v56, v48
	v_mov_b32_e32 v57, v48
	v_mov_b32_e32 v54, v48
	v_mov_b32_e32 v55, v48
	v_mov_b32_e32 v52, v48
	v_mov_b32_e32 v53, v48
	v_mov_b32_e32 v50, v48
	v_mov_b32_e32 v51, v48
	s_waitcnt lgkmcnt(0)
	s_barrier
.LBB0_676:
	v_mov_b32_e32 v46, s9
	ds_read_b128 v[20:23], v46
	ds_read_b128 v[0:3], v46 offset:512
	ds_read_b128 v[24:27], v46 offset:1024
	ds_read_b128 v[4:7], v46 offset:1536
	ds_read_b128 v[28:31], v46 offset:2048
	ds_read_b128 v[8:11], v46 offset:2560
	ds_read_b128 v[32:35], v46 offset:3072
	ds_read_b128 v[12:15], v46 offset:3584
	ds_read_b128 v[40:43], v46 offset:4096
	ds_read_b128 v[16:19], v46 offset:4608
	s_waitcnt lgkmcnt(9)
	v_mov_b32_e32 v76, v20
	s_waitcnt lgkmcnt(8)
	v_mov_b32_e32 v77, v0
	s_waitcnt lgkmcnt(7)
	v_mov_b32_e32 v78, v24
	s_waitcnt lgkmcnt(6)
	v_mov_b32_e32 v79, v4
	v_mov_b32_e32 v0, v21
	v_mov_b32_e32 v66, v22
	v_mov_b32_e32 v67, v2
	v_mov_b32_e32 v2, v23
	v_mov_b32_e32 v4, v25
	v_mov_b32_e32 v68, v26
	v_mov_b32_e32 v69, v6
	v_mov_b32_e32 v6, v27
	ds_read_b128 v[24:27], v46 offset:5120
	ds_read_b128 v[20:23], v46 offset:5632
	s_waitcnt lgkmcnt(7)
	v_mov_b32_e32 v80, v28
	s_waitcnt lgkmcnt(6)
	v_mov_b32_e32 v81, v8
	v_mov_b32_e32 v8, v29
	v_mov_b32_e32 v70, v30
	v_mov_b32_e32 v71, v10
	v_mov_b32_e32 v10, v31
	s_waitcnt lgkmcnt(3)
	v_mov_b32_e32 v84, v40
	s_waitcnt lgkmcnt(2)
	v_mov_b32_e32 v85, v16
	v_mov_b32_e32 v16, v41
	s_waitcnt lgkmcnt(1)
	v_mov_b32_e32 v86, v24
	s_waitcnt lgkmcnt(0)
	v_mov_b32_e32 v87, v20
	v_mov_b32_e32 v20, v25
	v_mov_b32_e32 v40, v26
	v_mov_b32_e32 v41, v22
	v_mov_b32_e32 v22, v27
	ds_read_b128 v[28:31], v46 offset:6144
	ds_read_b128 v[24:27], v46 offset:6656
	v_mov_b32_e32 v82, v32
	v_mov_b32_e32 v83, v12
	v_mov_b32_e32 v12, v33
	v_mov_b32_e32 v72, v34
	v_mov_b32_e32 v73, v14
	v_mov_b32_e32 v14, v35
	v_mov_b32_e32 v74, v42
	v_mov_b32_e32 v75, v18
	v_mov_b32_e32 v18, v43
	s_waitcnt lgkmcnt(1)
	v_mov_b32_e32 v88, v28
	s_waitcnt lgkmcnt(0)
	v_mov_b32_e32 v89, v24
	v_mov_b32_e32 v24, v29
	v_mov_b32_e32 v42, v30
	v_mov_b32_e32 v43, v26
	v_mov_b32_e32 v26, v31
	ds_read_b128 v[32:35], v46 offset:7168
	ds_read_b128 v[28:31], v46 offset:7680
	s_movk_i32 s10, 0x6000
	s_waitcnt lgkmcnt(1)
	v_mov_b32_e32 v90, v32
	s_waitcnt lgkmcnt(0)
	v_mov_b32_e32 v91, v28
	v_mov_b32_e32 v28, v33
	v_mov_b32_e32 v44, v34
	v_mov_b32_e32 v45, v30
	v_mov_b32_e32 v30, v35
	ds_read_b128 v[98:101], v46 offset:8192
	ds_read_b128 v[32:35], v46 offset:8704
	s_waitcnt lgkmcnt(1)
	v_mov_b32_e32 v92, v98
	s_waitcnt lgkmcnt(0)
	v_mov_b32_e32 v93, v32
	v_mov_b32_e32 v32, v99
	v_mov_b32_e32 v46, v100
	v_mov_b32_e32 v47, v34
	s_add_u32 s0, s0, 0xc000
	v_mov_b32_e32 v34, v101
	s_addc_u32 s1, s1, 0
	s_add_i32 s9, s9, 16
	s_cmp_eq_u32 s0, 0x180000
	s_cselect_b32 vcc_lo, 0, 0xc000
	s_add_u32 s100, s100, vcc_lo
	s_addc_u32 s101, s101, 0
	s_cmp_eq_u32 s0, 0x180000
	s_waitcnt vmcnt(3)
	v_pk_fma_f32 v[62:63], v[112:113], v[78:79], v[62:63] op_sel_hi:[0,1,1]
	v_pk_fma_f32 v[78:79], v[112:113], v[92:93], v[48:49] op_sel_hi:[0,1,1]
	v_pk_fma_f32 v[64:65], v[112:113], v[76:77], v[64:65] op_sel_hi:[0,1,1]
	v_pk_fma_f32 v[76:77], v[112:113], v[90:91], v[50:51] op_sel_hi:[0,1,1]
	s_mov_b32 s10, 0x9000
	v_pk_fma_f32 v[60:61], v[112:113], v[80:81], v[60:61] op_sel_hi:[0,1,1]
	v_pk_fma_f32 v[58:59], v[112:113], v[82:83], v[58:59] op_sel_hi:[0,1,1]
	v_pk_fma_f32 v[56:57], v[112:113], v[84:85], v[56:57] op_sel_hi:[0,1,1]
	v_pk_fma_f32 v[54:55], v[112:113], v[86:87], v[54:55] op_sel_hi:[0,1,1]
	v_pk_fma_f32 v[52:53], v[112:113], v[88:89], v[52:53] op_sel_hi:[0,1,1]
	global_load_dword v112, v110, s[100:101]
	s_waitcnt vmcnt(3)
	v_pk_fma_f32 v[64:65], v[114:115], v[0:1], v[64:65] op_sel_hi:[0,1,1]
	v_pk_fma_f32 v[62:63], v[114:115], v[4:5], v[62:63] op_sel_hi:[0,1,1]
	v_pk_fma_f32 v[60:61], v[114:115], v[8:9], v[60:61] op_sel_hi:[0,1,1]
	v_pk_fma_f32 v[58:59], v[114:115], v[12:13], v[58:59] op_sel_hi:[0,1,1]
	v_pk_fma_f32 v[56:57], v[114:115], v[16:17], v[56:57] op_sel_hi:[0,1,1]
	v_pk_fma_f32 v[0:1], v[114:115], v[20:21], v[54:55] op_sel_hi:[0,1,1]
	v_pk_fma_f32 v[4:5], v[114:115], v[24:25], v[52:53] op_sel_hi:[0,1,1]
	v_pk_fma_f32 v[8:9], v[114:115], v[28:29], v[76:77] op_sel_hi:[0,1,1]
	v_pk_fma_f32 v[12:13], v[114:115], v[32:33], v[78:79] op_sel_hi:[0,1,1]
	global_load_dword v114, v111, s[100:101]
	s_waitcnt vmcnt(3)
	v_pk_fma_f32 v[16:17], v[116:117], v[66:67], v[64:65] op_sel_hi:[0,1,1]
	v_pk_fma_f32 v[20:21], v[116:117], v[68:69], v[62:63] op_sel_hi:[0,1,1]
	v_pk_fma_f32 v[24:25], v[116:117], v[70:71], v[60:61] op_sel_hi:[0,1,1]
	v_pk_fma_f32 v[28:29], v[116:117], v[72:73], v[58:59] op_sel_hi:[0,1,1]
	v_pk_fma_f32 v[32:33], v[116:117], v[74:75], v[56:57] op_sel_hi:[0,1,1]
	v_pk_fma_f32 v[0:1], v[116:117], v[40:41], v[0:1] op_sel_hi:[0,1,1]
	v_pk_fma_f32 v[4:5], v[116:117], v[42:43], v[4:5] op_sel_hi:[0,1,1]
	v_pk_fma_f32 v[8:9], v[116:117], v[44:45], v[8:9] op_sel_hi:[0,1,1]
	v_pk_fma_f32 v[12:13], v[116:117], v[46:47], v[12:13] op_sel_hi:[0,1,1]
	global_load_dword v116, v106, s[100:101]
	s_waitcnt vmcnt(3)
	v_pk_fma_f32 v[64:65], v[118:119], v[2:3], v[16:17] op_sel_hi:[0,1,1]
	v_pk_fma_f32 v[62:63], v[118:119], v[6:7], v[20:21] op_sel_hi:[0,1,1]
	v_pk_fma_f32 v[60:61], v[118:119], v[10:11], v[24:25] op_sel_hi:[0,1,1]
	v_pk_fma_f32 v[58:59], v[118:119], v[14:15], v[28:29] op_sel_hi:[0,1,1]
	v_pk_fma_f32 v[56:57], v[118:119], v[18:19], v[32:33] op_sel_hi:[0,1,1]
	v_pk_fma_f32 v[54:55], v[118:119], v[22:23], v[0:1] op_sel_hi:[0,1,1]
	v_pk_fma_f32 v[52:53], v[118:119], v[26:27], v[4:5] op_sel_hi:[0,1,1]
	v_pk_fma_f32 v[50:51], v[118:119], v[30:31], v[8:9] op_sel_hi:[0,1,1]
	v_pk_fma_f32 v[48:49], v[118:119], v[34:35], v[12:13] op_sel_hi:[0,1,1]
	global_load_dword v118, v107, s[100:101]
	s_cbranch_scc0 .LBB0_676
; __device__ __forceinline__ void phase_init(const Params& p, LAS unsigned char* lds) {
;     ...
;     for (int u = b; u < 96; u += nb) {
;         const int cb = u % 6, ks = (u / 6) % 8, l = u / 48;
;     ...
;         for (int s = 0; s < 18; ++s) adap[(size_t)((ks * 2 + l) * 18 + s) * 3072 + n] = acc[s];
	s_lshl_b32 s0, s6, 1
	s_add_i32 s0, s0, s8
	s_mul_i32 s6, s0, 18
	v_lshl_add_u64 v[0:1], v[36:37], 2, s[98:99]
	v_mad_i64_i32 v[2:3], s[0:1], s6, v250, v[0:1]
	s_or_b32 s0, s6, 1
	global_store_dword v[2:3], v64, off
	v_mad_i64_i32 v[2:3], s[0:1], s0, v250, v[0:1]
	s_add_i32 s0, s6, 2
	global_store_dword v[2:3], v65, off
	v_mad_i64_i32 v[2:3], s[0:1], s0, v250, v[0:1]
	s_add_i32 s0, s6, 3
	global_store_dword v[2:3], v62, off
	v_mad_i64_i32 v[2:3], s[0:1], s0, v250, v[0:1]
	s_add_i32 s0, s6, 4
	global_store_dword v[2:3], v63, off
	v_mad_i64_i32 v[2:3], s[0:1], s0, v250, v[0:1]
	s_add_i32 s0, s6, 5
	global_store_dword v[2:3], v60, off
	v_mad_i64_i32 v[2:3], s[0:1], s0, v250, v[0:1]
	s_add_i32 s0, s6, 6
	global_store_dword v[2:3], v61, off
	v_mad_i64_i32 v[2:3], s[0:1], s0, v250, v[0:1]
	s_add_i32 s0, s6, 7
	global_store_dword v[2:3], v58, off
	v_mad_i64_i32 v[2:3], s[0:1], s0, v250, v[0:1]
	s_add_i32 s0, s6, 8
	global_store_dword v[2:3], v59, off
	v_mad_i64_i32 v[2:3], s[0:1], s0, v250, v[0:1]
	s_add_i32 s0, s6, 9
	global_store_dword v[2:3], v56, off
	v_mad_i64_i32 v[2:3], s[0:1], s0, v250, v[0:1]
	s_add_i32 s0, s6, 10
	global_store_dword v[2:3], v57, off
	v_mad_i64_i32 v[2:3], s[0:1], s0, v250, v[0:1]
	s_add_i32 s0, s6, 11
	global_store_dword v[2:3], v54, off
	v_mad_i64_i32 v[2:3], s[0:1], s0, v250, v[0:1]
	s_add_i32 s0, s6, 12
	global_store_dword v[2:3], v55, off
	v_mad_i64_i32 v[2:3], s[0:1], s0, v250, v[0:1]
	s_add_i32 s0, s6, 13
	global_store_dword v[2:3], v52, off
	v_mad_i64_i32 v[2:3], s[0:1], s0, v250, v[0:1]
	s_add_i32 s0, s6, 14
	global_store_dword v[2:3], v53, off
	v_mad_i64_i32 v[2:3], s[0:1], s0, v250, v[0:1]
	s_add_i32 s0, s6, 15
	global_store_dword v[2:3], v50, off
	v_mad_i64_i32 v[2:3], s[0:1], s0, v250, v[0:1]
	s_add_i32 s0, s6, 16
	s_add_i32 s6, s6, 17
	s_add_i32 s4, s4, s96
	global_store_dword v[2:3], v51, off
	v_mad_i64_i32 v[2:3], s[0:1], s0, v250, v[0:1]
	v_mad_i64_i32 v[0:1], s[0:1], s6, v250, v[0:1]
	s_cmpk_gt_i32 s4, 0x5f
	global_store_dword v[2:3], v48, off
	global_store_dword v[0:1], v49, off
	s_cbranch_scc0 .LBB0_672
